# grid barrier spin loops poll less often (s_sleep 3 instead of 1): less traffic on the release words
# baseline (speedup 1.0000x reference)
.LBB0_196:
	s_and_b32 s6, s2, 0xff
	s_mov_b64 s[34:35], -1
	s_cmp_lg_u32 s6, 0
	s_mov_b64 s[40:41], -1
	s_sleep 3
	s_cbranch_scc1 .LBB0_199
	v_readlane_b32 s6, v253, 48
	v_readlane_b32 s7, v253, 49
	s_nop 4
	global_load_dword v2, v1, s[6:7] sc1
	s_waitcnt vmcnt(0)
	v_cmp_eq_u32_e32 vcc, 0, v2
	s_cbranch_vccnz .LBB0_201
	s_mov_b64 s[40:41], 0
	s_mov_b64 s[38:39], -1
